# adaLN publish no longer does an L2 writeback: phase-0 stores are written through (sc0 sc1), so a vmcnt(0) + counter is enough; P1 on every WG starts earlier
# speedup vs baseline: 1.0071x; 1.0052x over previous
; __device__ __forceinline__ void phase0(const Ptrs& P, LAS unsigned char* lds, int G) {
;     ...
;     if (blockIdx.x < 96) {
;         asm volatile("s_waitcnt vmcnt(0)" ::: "memory"); __syncthreads();
;         if (tid == 0) { __builtin_amdgcn_fence(__ATOMIC_RELEASE, "agent"); asm volatile("s_waitcnt vmcnt(0)" ::: "memory");
;             __hip_atomic_fetch_add((unsigned*)(P.ws + WS_BAR) + 3520, 1u, __ATOMIC_RELAXED, __HIP_MEMORY_SCOPE_AGENT); }
.LBB0_65:
	s_waitcnt vmcnt(0)
	s_barrier
	s_mov_b64 s[0:1], exec
	v_readlane_b32 s2, v254, 5
	v_readlane_b32 s3, v254, 6
	s_and_b64 s[2:3], s[0:1], s[2:3]
	s_mov_b64 exec, s[2:3]
	s_cbranch_execz .LBB0_68
	s_mov_b64 s[2:3], exec
	v_mbcnt_lo_u32_b32 v0, s2, 0
	s_waitcnt vmcnt(0)
	s_waitcnt vmcnt(0)
	v_mbcnt_hi_u32_b32 v0, s3, v0
	v_cmp_eq_u32_e32 vcc, 0, v0
	s_and_b64 s[4:5], exec, vcc
	s_mov_b64 exec, s[4:5]
	s_cbranch_execz .LBB0_68
	s_bcnt1_i32_b64 s2, s[2:3]
	v_mov_b32_e32 v0, 0x73000
	v_mov_b32_e32 v1, s2
	global_atomic_add v0, v1, s[90:91] offset:1792
